# token-shift prep loop: software prefetch of row k+2 into L2 (1 dword/lane at 64 B stride), wait relaxed by one
# baseline (speedup 1.0000x reference)
.LBB0_873:
	v_mov_b64_e32 v[100:101], v[104:105]
	v_mov_b64_e32 v[102:103], v[106:107]
	v_mov_b64_e32 v[104:105], v[112:113]
	v_mov_b64_e32 v[106:107], v[114:115]
	v_mov_b64_e32 v[112:113], v[132:133]
	v_mov_b64_e32 v[114:115], v[134:135]
	v_mov_b64_e32 v[132:133], v[144:145]
	s_add_i32 s100, s5, 2
	v_readlane_b32 s101, v253, 16
	s_add_i32 s101, s101, -1
	s_min_u32 s100, s100, s101
	v_add_u32_e32 v236, s100, v148
	v_mov_b32_e32 v237, 0
	v_mul_u32_u24_e32 v238, 48, v224
	v_lshlrev_b64 v[236:237], 12, v[236:237]
	v_mov_b32_e32 v239, 0
	v_lshl_add_u64 v[236:237], v[2:3], 0, v[236:237]
	v_lshl_add_u64 v[236:237], v[236:237], 0, v[238:239]
	global_load_dword v240, v[236:237], off
	s_waitcnt vmcnt(5)
	v_mov_b64_e32 v[108:109], v[116:117]
	s_and_b64 vcc, exec, s[8:9]
	v_mov_b64_e32 v[134:135], v[146:147]
	v_mov_b64_e32 v[212:213], v[196:197]
	v_mov_b64_e32 v[208:209], v[192:193]
	v_mov_b64_e32 v[204:205], v[188:189]
	v_mov_b64_e32 v[200:201], v[184:185]
	v_mov_b64_e32 v[214:215], v[198:199]
	v_mov_b64_e32 v[210:211], v[194:195]
	v_mov_b64_e32 v[206:207], v[190:191]
	v_mov_b64_e32 v[202:203], v[186:187]
	s_mov_b32 s5, s4
	v_mov_b64_e32 v[110:111], v[118:119]
	v_mov_b32_e32 v144, v128
	v_mov_b32_e32 v145, v129
	v_mov_b32_e32 v146, v130
	v_mov_b32_e32 v147, v131
	v_mov_b32_e32 v140, v124
	v_mov_b32_e32 v141, v125
	v_mov_b32_e32 v142, v126
	v_mov_b32_e32 v143, v127
	v_mov_b32_e32 v136, v120
	v_mov_b32_e32 v137, v121
	v_mov_b32_e32 v138, v122
	v_mov_b32_e32 v139, v123
	v_mov_b32_e32 v216, v116
	v_mov_b32_e32 v217, v117
	v_mov_b32_e32 v218, v118
	v_mov_b32_e32 v219, v119
	s_cbranch_vccnz .LBB0_895
